# LRU scan loop: output stores through one running scalar base (SADDR), conv-input row addresses chained by +pitch, gate-value loads with SGPR-pair constants (fewer VALU address instructions)
# speedup vs baseline: 1.0011x; 1.0009x over previous
.LBB0_863:
	s_or_b64 exec, exec, s[18:19]
	s_and_b32 s18, s21, 3
	s_ashr_i32 s27, s27, 6
	v_bfe_u32 v140, v137, 4, 2
	s_lshl_b32 s28, s18, 6
	s_lshl_b64 s[18:19], s[16:17], 23
	s_lshl_b32 s16, s27, 4
	v_lshl_or_b32 v143, v140, 2, s16
	v_lshl_or_b32 v138, s27, 2, v140
	v_ashrrev_i32_e32 v144, 3, v143
	s_movk_i32 s17, 0x90
	s_lshr_b32 s12, s22, 2
	v_mul_lo_u32 v145, v138, s17
	v_mad_u32_u24 v144, v136, s17, v144
	v_lshlrev_b32_e32 v140, 6, v140
	s_movk_i32 s17, 0x50
	s_and_b32 s12, s12, 3
	v_bitop3_b32 v149, v140, s17, 16 bitop3:0xc8
	s_movk_i32 s17, 0x60
	s_lshl_b32 s12, s12, 8
	v_bitop3_b32 v150, v140, s17, 32 bitop3:0xc8
	s_movk_i32 s17, 0x70
	v_and_b32_e32 v148, 64, v140
	v_bitop3_b32 v140, v140, s17, 48 bitop3:0xc8
	s_add_u32 s14, s14, s28
	v_add_u32_e32 v166, v144, v148
	v_add_u32_e32 v167, v149, v144
	v_add_u32_e32 v168, v150, v144
	v_add_u32_e32 v169, v140, v144
	v_add_u32_e32 v144, 0x900, v144
	v_cmp_gt_u32_e64 s[44:45], 2, v136
	s_addc_u32 s15, s15, 0
	v_and_b32_e32 v139, 63, v137
	v_add_u32_e32 v173, v140, v144
	v_cndmask_b32_e64 v140, -2, 0, s[44:45]
	v_cmp_gt_u32_e64 s[46:47], 4, v136
	s_add_u32 s12, s14, s12
	v_cmp_ne_u32_e64 s[40:41], 0, v136
	v_add_lshl_u32 v174, v140, v139, 2
	v_cndmask_b32_e64 v140, -4, 0, s[46:47]
	s_addc_u32 s17, s15, 0
	v_or_b32_e32 v163, v145, v136
	v_subbrev_co_u32_e64 v145, vcc, 0, v139, s[40:41]
	v_lshl_or_b32 v165, v139, 2, 60
	v_add_lshl_u32 v175, v140, v139, 2
	v_ashrrev_i32_e32 v139, 31, v138
	s_add_u32 s14, s12, s18
	v_or_b32_e32 v146, s24, v136
	v_add_u32_e32 v172, v150, v144
	v_lshlrev_b64 v[150:151], 1, v[138:139]
	v_lshlrev_b32_e32 v138, 15, v136
	v_mov_b32_e32 v139, v203
	s_addc_u32 s15, s17, s19
	v_or_b32_e32 v142, s16, v136
	s_movk_i32 s27, 0x110
	v_lshlrev_b32_e32 v146, 1, v146
	v_lshl_add_u64 v[152:153], s[14:15], 0, v[138:139]
	s_add_u32 s100, s14, 0x3dc00000
	s_addc_u32 s101, s15, 0
	v_add_u32_e32 v250, v138, v150
	s_add_u32 s14, s12, s26
	v_mul_lo_u32 v142, v142, s27
	v_add_u32_e32 v147, 0, v146
	v_or_b32_e32 v146, 32, v146
	s_addc_u32 s15, s17, s25
	v_lshl_add_u32 v141, v136, 4, 0
	v_add_u32_e32 v142, 0, v142
	v_lshlrev_b32_e32 v164, 2, v145
	v_mul_lo_u32 v145, v162, s27
	v_mul_lo_u32 v135, v135, s27
	v_mul_lo_u32 v143, v143, s27
	v_add_u32_e32 v146, 0, v146
	v_lshlrev_b32_e32 v137, 2, v137
	v_mov_b64_e32 v[138:139], s[14:15]
	s_mov_b32 s12, 0x14000
	s_mov_b32 s16, 0
	v_cmp_eq_u32_e64 s[42:43], 0, v136
	v_add_u32_e32 v170, v144, v148
	v_add_u32_e32 v171, v149, v144
	v_cmp_gt_u32_e64 s[48:49], 8, v136
	v_and_b32_e32 v176, 0xdc, v137
	v_mad_u64_u32 v[154:155], s[14:15], v136, s12, v[138:139]
	v_mov_b32_e32 v178, 0
	v_add_u32_e32 v177, v141, v145
	v_add_u32_e32 v179, v141, v135
	v_add_u32_e32 v180, v142, v134
	v_add_u32_e32 v181, v147, v143
	v_add_u32_e32 v182, v146, v143
	s_mov_b32 s17, 0
	s_branch .LBB0_865
.LBB0_864:
	s_or_b64 exec, exec, s[14:15]
	v_add_f32_e32 v136, v159, v137
	v_mul_f32_e32 v136, 0xbfb8aa3b, v136
	v_exp_f32_e32 v136, v136
	ds_read_u16 v137, v182 offset:816
	v_sqrt_f32_e32 v135, v135
	v_lshl_add_u32 v138, v173, 2, s12
	v_add_f32_e32 v136, 1.0, v136
	v_rcp_f32_e32 v136, v136
	s_waitcnt lgkmcnt(0)
	v_lshlrev_b32_e32 v137, 16, v137
	s_waitcnt vmcnt(7)
	v_lshlrev_b32_e32 v190, 16, v190
	s_waitcnt vmcnt(6)
	v_lshlrev_b32_e32 v189, 16, v189
	v_mul_f32_e32 v136, v136, v137
	v_mul_f32_e32 v135, v135, v136
	ds_write2st64_b32 v138, v134, v135 offset0:136 offset1:208
	v_lshl_add_u32 v134, v163, 2, s12
	s_waitcnt lgkmcnt(0)
	s_barrier
	v_add_u32_e32 v135, 0x8800, v134
	v_add_u32_e32 v136, 0xd000, v134
	ds_read2_b32 v[138:139], v135 offset1:16
	ds_read2_b32 v[140:141], v136 offset1:16
	ds_read2_b32 v[142:143], v135 offset0:32 offset1:48
	ds_read2_b32 v[144:145], v136 offset0:32 offset1:48
	ds_read2_b32 v[146:147], v135 offset0:64 offset1:80
	ds_read2_b32 v[148:149], v136 offset0:64 offset1:80
	s_mov_b32 s12, 0x3dc00000
	s_waitcnt lgkmcnt(3)
	v_mov_b32_e32 v195, v142
	v_mul_f32_e32 v193, v138, v139
	v_fma_f32 v134, 0, v138, v140
	v_fma_f32 v134, v134, v139, v141
	s_waitcnt lgkmcnt(2)
	v_fma_f32 v134, v134, v142, v144
	v_fma_f32 v134, v134, v143, v145
	s_waitcnt lgkmcnt(0)
	v_fma_f32 v192, v134, v146, v148
	ds_read2_b32 v[134:135], v135 offset0:96 offset1:112
	ds_read2_b32 v[136:137], v136 offset0:96 offset1:112
	v_mov_b32_e32 v194, v147
	v_pk_mul_f32 v[196:197], v[192:193], v[194:195]
	v_mov_b32_e32 v198, v149
	v_mov_b32_e32 v200, v149
	v_mov_b32_e32 v201, v143
	v_pk_fma_f32 v[192:193], v[192:193], v[194:195], v[198:199]
	v_pk_mul_f32 v[194:195], v[196:197], v[200:201]
	s_waitcnt lgkmcnt(1)
	v_mov_b32_e32 v196, v134
	v_mov_b32_e32 v197, v146
	v_mov_b32_e32 v193, v195
	v_pk_mul_f32 v[194:195], v[194:195], v[196:197]
	s_waitcnt lgkmcnt(0)
	v_mov_b32_e32 v198, v136
	v_mov_b32_e32 v199, v147
	v_pk_fma_f32 v[192:193], v[192:193], v[196:197], v[136:137]
	v_pk_mul_f32 v[194:195], v[194:195], v[198:199]
	s_addk_i32 s17, 0x80
	v_mov_b32_e32 v193, v195
	v_mov_b32_e32 v194, v135
	v_mov_b32_e32 v195, v134
	v_pk_mul_f32 v[192:193], v[192:193], v[194:195]
	s_mov_b64 s[14:15], 0x80000
	v_mul_f32_e32 v191, v193, v135
	v_add_f32_e32 v192, v192, v137
	s_add_i32 s16, s16, 64
	s_cmpk_lg_i32 s17, 0x800
	v_lshl_add_u64 v[154:155], v[154:155], 0, s[36:37]
	s_nop 1
	v_fmac_f32_dpp v192, v192, v191 row_shr:1 row_mask:0xf bank_mask:0xf
	v_mul_f32_dpp v191, v191, v191 row_shr:1 row_mask:0xf bank_mask:0xf
	s_nop 1
	v_fmac_f32_dpp v192, v192, v191 row_shr:2 row_mask:0xf bank_mask:0xf
	v_mul_f32_dpp v191, v191, v191 row_shr:2 row_mask:0xf bank_mask:0xf
	s_nop 1
	v_fmac_f32_dpp v192, v192, v191 row_shr:4 row_mask:0xf bank_mask:0xf
	v_mul_f32_dpp v191, v191, v191 row_shr:4 row_mask:0xf bank_mask:0xf
	s_nop 1
	v_fmac_f32_dpp v192, v192, v191 row_shr:8 row_mask:0xf bank_mask:0xf
	v_mul_f32_dpp v191, v191, v191 row_shr:8 row_mask:0xf bank_mask:0xf
	v_fmac_f32_e32 v192, v178, v191
	v_mul_f32_e32 v191, v190, v190
	v_fmamk_f32 v191, v191, 0xbdd2d3e7, v228
	v_mul_f32_e32 v191, v191, v190
	v_exp_f32_e32 v191, v191
	v_mov_b32_dpp v193, v192 row_shr:1 row_mask:0xf bank_mask:0xf
	v_add_f32_e32 v191, 1.0, v191
	v_rcp_f32_e32 v191, v191
	v_cndmask_b32_e64 v193, v193, v178, s[42:43]
	v_fma_f32 v138, v138, v193, v140
	ds_bpermute_b32 v178, v165, v192
	v_mul_f32_e32 v140, v191, v190
	v_mul_f32_e32 v190, v189, v189
	v_fmamk_f32 v190, v190, 0xbdd2d3e7, v228
	v_mul_f32_e32 v190, v190, v189
	v_exp_f32_e32 v192, v190
	v_mul_f32_e32 v140, v140, v138
	v_bfe_u32 v190, v140, 16, 1
	v_add3_u32 v140, v140, v190, s0
	v_add_f32_e32 v192, 1.0, v192
	v_rcp_f32_e32 v194, v192
	v_fmac_f32_e32 v141, v139, v138
	global_store_short_d16_hi v250, v140, s[100:101] offset:3072
	s_add_u32 s100, s100, 0x1000
	s_addc_u32 s101, s101, 0
	s_waitcnt vmcnt(6)
	v_lshlrev_b32_e32 v140, 16, v188
	v_mul_f32_e32 v139, v140, v140
	v_fmamk_f32 v139, v139, 0xbdd2d3e7, v228
	v_mul_f32_e32 v139, v139, v140
	v_exp_f32_e32 v139, v139
	v_mul_f32_e32 v138, v194, v189
	v_mul_f32_e32 v138, v138, v141
	v_bfe_u32 v188, v138, 16, 1
	v_add3_u32 v188, v138, v188, s0
	v_add_f32_e32 v138, 1.0, v139
	v_rcp_f32_e32 v189, v138
	s_mov_b32 s12, 0x3dc01000
	v_fma_f32 v141, v142, v141, v144
	global_store_short_d16_hi v250, v188, s[100:101] offset:3072
	s_add_u32 s100, s100, 0x1000
	s_addc_u32 s101, s101, 0
	v_mul_f32_e32 v138, v189, v140
	s_waitcnt vmcnt(6)
	v_lshlrev_b32_e32 v140, 16, v187
	v_mul_f32_e32 v139, v140, v140
	v_fmamk_f32 v139, v139, 0xbdd2d3e7, v228
	v_mul_f32_e32 v139, v139, v140
	v_exp_f32_e32 v139, v139
	v_mul_f32_e32 v138, v138, v141
	v_bfe_u32 v142, v138, 16, 1
	v_add3_u32 v142, v138, v142, s0
	v_add_f32_e32 v138, 1.0, v139
	v_rcp_f32_e32 v144, v138
	s_mov_b32 s12, 0x3dc02000
	v_fmac_f32_e32 v145, v143, v141
	global_store_short_d16_hi v250, v142, s[100:101] offset:3072
	s_add_u32 s100, s100, 0x1000
	s_addc_u32 s101, s101, 0
	v_mul_f32_e32 v138, v144, v140
	s_waitcnt vmcnt(6)
	v_lshlrev_b32_e32 v140, 16, v186
	v_mul_f32_e32 v139, v140, v140
	v_fmamk_f32 v139, v139, 0xbdd2d3e7, v228
	v_mul_f32_e32 v139, v139, v140
	v_exp_f32_e32 v139, v139
	v_mul_f32_e32 v138, v138, v145
	v_bfe_u32 v141, v138, 16, 1
	v_add3_u32 v141, v138, v141, s0
	v_add_f32_e32 v138, 1.0, v139
	v_rcp_f32_e32 v142, v138
	s_mov_b32 s12, 0x3dc03000
	s_mov_b32 s12, 0x3dc04000
	global_store_short_d16_hi v250, v141, s[100:101] offset:3072
	s_add_u32 s100, s100, 0x1000
	s_addc_u32 s101, s101, 0
	v_mul_f32_e32 v138, v142, v140
	s_waitcnt vmcnt(6)
	v_lshlrev_b32_e32 v140, 16, v185
	v_mul_f32_e32 v139, v140, v140
	v_fmamk_f32 v139, v139, 0xbdd2d3e7, v228
	v_mul_f32_e32 v139, v139, v140
	v_exp_f32_e32 v139, v139
	v_fma_f32 v141, v146, v145, v148
	v_mul_f32_e32 v138, v138, v141
	v_bfe_u32 v142, v138, 16, 1
	v_add3_u32 v142, v138, v142, s0
	v_add_f32_e32 v138, 1.0, v139
	v_rcp_f32_e32 v143, v138
	v_fmac_f32_e32 v149, v147, v141
	global_store_short_d16_hi v250, v142, s[100:101] offset:3072
	s_add_u32 s100, s100, 0x1000
	s_addc_u32 s101, s101, 0
	v_mul_f32_e32 v138, v143, v140
	s_waitcnt vmcnt(6)
	v_lshlrev_b32_e32 v140, 16, v183
	v_mul_f32_e32 v139, v140, v140
	v_fmamk_f32 v139, v139, 0xbdd2d3e7, v228
	v_mul_f32_e32 v139, v139, v140
	v_exp_f32_e32 v139, v139
	v_mul_f32_e32 v138, v138, v149
	v_bfe_u32 v141, v138, 16, 1
	v_add3_u32 v141, v138, v141, s0
	v_add_f32_e32 v138, 1.0, v139
	v_rcp_f32_e32 v142, v138
	s_mov_b32 s12, 0x3dc05000
	v_fma_f32 v134, v134, v149, v136
	v_mul_f32_e32 v136, v142, v140
	s_waitcnt vmcnt(5)
	v_lshlrev_b32_e32 v140, 16, v184
	global_store_short_d16_hi v250, v141, s[100:101] offset:3072
	s_add_u32 s100, s100, 0x1000
	s_addc_u32 s101, s101, 0
	v_mul_f32_e32 v138, v140, v140
	v_fmamk_f32 v138, v138, 0xbdd2d3e7, v228
	v_mul_f32_e32 v138, v138, v140
	v_exp_f32_e32 v138, v138
	v_mul_f32_e32 v136, v136, v134
	s_mov_b32 s12, 0x3dc06000
	v_fmac_f32_e32 v137, v135, v134
	v_add_f32_e32 v138, 1.0, v138
	v_rcp_f32_e32 v141, v138
	v_bfe_u32 v139, v136, 16, 1
	v_mul_f32_e32 v134, v141, v140
	v_mul_f32_e32 v134, v134, v137
	v_add3_u32 v136, v136, v139, s0
	v_bfe_u32 v135, v134, 16, 1
	global_store_short_d16_hi v250, v136, s[100:101] offset:3072
	s_add_u32 s100, s100, 0x1000
	s_addc_u32 s101, s101, 0
	v_add3_u32 v136, v134, v135, s0
	global_store_short_d16_hi v250, v136, s[100:101] offset:3072
	s_add_u32 s100, s100, 0x79000
	s_addc_u32 s101, s101, 0
	s_cmpk_lg_i32 s17, 0x800
	s_cbranch_scc0 .LBB0_848
.LBB0_865:
	s_waitcnt vmcnt(0)
	v_lshlrev_b32_e32 v134, 16, v110
	v_and_b32_e32 v135, 0xffff0000, v110
	v_lshlrev_b32_e32 v136, 16, v111
	v_and_b32_e32 v137, 0xffff0000, v111
	v_lshlrev_b32_e32 v184, 16, v112
	v_and_b32_e32 v185, 0xffff0000, v112
	v_lshlrev_b32_e32 v192, 16, v113
	v_and_b32_e32 v193, 0xffff0000, v113
	v_pk_fma_f32 v[134:135], v[70:71], v[134:135], v[102:103]
	v_lshlrev_b32_e32 v138, 16, v106
	v_and_b32_e32 v139, 0xffff0000, v106
	v_pk_fma_f32 v[136:137], v[72:73], v[136:137], v[104:105]
	v_lshlrev_b32_e32 v144, 16, v107
	v_and_b32_e32 v145, 0xffff0000, v107
	v_pk_fma_f32 v[184:185], v[66:67], v[184:185], v[98:99]
	v_lshlrev_b32_e32 v186, 16, v108
	v_and_b32_e32 v187, 0xffff0000, v108
	v_pk_fma_f32 v[192:193], v[68:69], v[192:193], v[100:101]
	v_lshlrev_b32_e32 v194, 16, v109
	v_and_b32_e32 v195, 0xffff0000, v109
	v_pk_fma_f32 v[134:135], v[78:79], v[138:139], v[134:135]
	v_lshlrev_b32_e32 v140, 16, v118
	v_and_b32_e32 v141, 0xffff0000, v118
	v_pk_fma_f32 v[136:137], v[80:81], v[144:145], v[136:137]
	v_lshlrev_b32_e32 v146, 16, v119
	v_and_b32_e32 v147, 0xffff0000, v119
	v_pk_fma_f32 v[184:185], v[74:75], v[186:187], v[184:185]
	v_lshlrev_b32_e32 v188, 16, v120
	v_and_b32_e32 v189, 0xffff0000, v120
	v_pk_fma_f32 v[192:193], v[76:77], v[194:195], v[192:193]
	v_lshlrev_b32_e32 v196, 16, v121
	v_and_b32_e32 v197, 0xffff0000, v121
	v_pk_fma_f32 v[134:135], v[82:83], v[140:141], v[134:135]
	v_lshlrev_b32_e32 v142, 16, v114
	v_and_b32_e32 v143, 0xffff0000, v114
	v_pk_fma_f32 v[136:137], v[84:85], v[146:147], v[136:137]
	v_lshlrev_b32_e32 v148, 16, v115
	v_and_b32_e32 v149, 0xffff0000, v115
	v_pk_fma_f32 v[184:185], v[90:91], v[188:189], v[184:185]
	v_lshlrev_b32_e32 v190, 16, v116
	v_and_b32_e32 v191, 0xffff0000, v116
	v_pk_fma_f32 v[192:193], v[92:93], v[196:197], v[192:193]
	v_lshlrev_b32_e32 v198, 16, v117
	v_and_b32_e32 v199, 0xffff0000, v117
	v_pk_fma_f32 v[134:135], v[86:87], v[142:143], v[134:135]
	v_pk_fma_f32 v[136:137], v[88:89], v[148:149], v[136:137]
	v_pk_fma_f32 v[184:185], v[94:95], v[190:191], v[184:185]
	v_pk_fma_f32 v[192:193], v[96:97], v[198:199], v[192:193]
	v_cvt_pk_bf16_f32 v134, v134, v135
	v_cvt_pk_bf16_f32 v135, v136, v137
	v_cvt_pk_bf16_f32 v136, v184, v185
	v_cvt_pk_bf16_f32 v137, v192, v193
	ds_write_b128 v177, v[134:137]
	v_pk_fma_f32 v[134:135], v[70:71], v[138:139], v[102:103]
	v_pk_fma_f32 v[136:137], v[72:73], v[144:145], v[104:105]
	v_pk_fma_f32 v[184:185], v[66:67], v[186:187], v[98:99]
	v_pk_fma_f32 v[192:193], v[68:69], v[194:195], v[100:101]
	v_pk_fma_f32 v[134:135], v[78:79], v[140:141], v[134:135]
	v_pk_fma_f32 v[136:137], v[80:81], v[146:147], v[136:137]
	v_pk_fma_f32 v[184:185], v[74:75], v[188:189], v[184:185]
	v_pk_fma_f32 v[192:193], v[76:77], v[196:197], v[192:193]
	v_pk_fma_f32 v[134:135], v[82:83], v[142:143], v[134:135]
	v_lshlrev_b32_e32 v138, 16, v126
	v_and_b32_e32 v139, 0xffff0000, v126
	v_pk_fma_f32 v[136:137], v[84:85], v[148:149], v[136:137]
	v_lshlrev_b32_e32 v144, 16, v127
	v_and_b32_e32 v145, 0xffff0000, v127
	v_pk_fma_f32 v[184:185], v[90:91], v[190:191], v[184:185]
	v_lshlrev_b32_e32 v186, 16, v128
	v_and_b32_e32 v187, 0xffff0000, v128
	v_pk_fma_f32 v[192:193], v[92:93], v[198:199], v[192:193]
	v_lshlrev_b32_e32 v194, 16, v129
	v_and_b32_e32 v195, 0xffff0000, v129
	v_pk_fma_f32 v[134:135], v[86:87], v[138:139], v[134:135]
	v_pk_fma_f32 v[136:137], v[88:89], v[144:145], v[136:137]
	v_pk_fma_f32 v[184:185], v[94:95], v[186:187], v[184:185]
	v_pk_fma_f32 v[192:193], v[96:97], v[194:195], v[192:193]
	v_cvt_pk_bf16_f32 v134, v134, v135
	v_cvt_pk_bf16_f32 v135, v136, v137
	v_cvt_pk_bf16_f32 v136, v184, v185
	v_cvt_pk_bf16_f32 v137, v192, v193
	ds_write_b128 v177, v[134:137] offset:272
	v_pk_fma_f32 v[134:135], v[70:71], v[140:141], v[102:103]
	v_pk_fma_f32 v[136:137], v[72:73], v[146:147], v[104:105]
	v_pk_fma_f32 v[184:185], v[66:67], v[188:189], v[98:99]
	v_pk_fma_f32 v[192:193], v[68:69], v[196:197], v[100:101]
	v_pk_fma_f32 v[134:135], v[78:79], v[142:143], v[134:135]
	v_pk_fma_f32 v[136:137], v[80:81], v[148:149], v[136:137]
	v_pk_fma_f32 v[184:185], v[74:75], v[190:191], v[184:185]
	v_pk_fma_f32 v[192:193], v[76:77], v[198:199], v[192:193]
	v_pk_fma_f32 v[134:135], v[82:83], v[138:139], v[134:135]
	v_lshlrev_b32_e32 v140, 16, v122
	v_and_b32_e32 v141, 0xffff0000, v122
	v_pk_fma_f32 v[136:137], v[84:85], v[144:145], v[136:137]
	v_lshlrev_b32_e32 v146, 16, v123
	v_and_b32_e32 v147, 0xffff0000, v123
	v_pk_fma_f32 v[184:185], v[90:91], v[186:187], v[184:185]
	v_lshlrev_b32_e32 v188, 16, v124
	v_and_b32_e32 v189, 0xffff0000, v124
	v_pk_fma_f32 v[192:193], v[92:93], v[194:195], v[192:193]
	v_lshlrev_b32_e32 v196, 16, v125
	v_and_b32_e32 v197, 0xffff0000, v125
	v_pk_fma_f32 v[134:135], v[86:87], v[140:141], v[134:135]
	v_pk_fma_f32 v[136:137], v[88:89], v[146:147], v[136:137]
	v_pk_fma_f32 v[184:185], v[94:95], v[188:189], v[184:185]
	v_pk_fma_f32 v[192:193], v[96:97], v[196:197], v[192:193]
	v_cvt_pk_bf16_f32 v134, v134, v135
	v_cvt_pk_bf16_f32 v135, v136, v137
	v_cvt_pk_bf16_f32 v136, v184, v185
	v_cvt_pk_bf16_f32 v137, v192, v193
	ds_write_b128 v177, v[134:137] offset:544
	v_pk_fma_f32 v[134:135], v[70:71], v[142:143], v[102:103]
	v_lshlrev_b32_e32 v136, 16, v130
	v_pk_fma_f32 v[134:135], v[78:79], v[138:139], v[134:135]
	v_and_b32_e32 v137, 0xffff0000, v130
	v_pk_fma_f32 v[134:135], v[82:83], v[140:141], v[134:135]
	v_lshlrev_b32_e32 v138, 16, v131
	v_pk_fma_f32 v[134:135], v[86:87], v[136:137], v[134:135]
	v_pk_fma_f32 v[136:137], v[72:73], v[148:149], v[104:105]
	v_and_b32_e32 v139, 0xffff0000, v131
	v_pk_fma_f32 v[136:137], v[80:81], v[144:145], v[136:137]
	v_lshlrev_b32_e32 v140, 16, v132
	v_pk_fma_f32 v[136:137], v[84:85], v[146:147], v[136:137]
	v_and_b32_e32 v141, 0xffff0000, v132
	v_pk_fma_f32 v[136:137], v[88:89], v[138:139], v[136:137]
	v_pk_fma_f32 v[138:139], v[66:67], v[190:191], v[98:99]
	v_lshlrev_b32_e32 v142, 16, v133
	v_pk_fma_f32 v[138:139], v[74:75], v[186:187], v[138:139]
	v_and_b32_e32 v143, 0xffff0000, v133
	v_pk_fma_f32 v[138:139], v[90:91], v[188:189], v[138:139]
	v_cvt_pk_bf16_f32 v134, v134, v135
	v_pk_fma_f32 v[138:139], v[94:95], v[140:141], v[138:139]
	v_pk_fma_f32 v[140:141], v[68:69], v[198:199], v[100:101]
	v_cvt_pk_bf16_f32 v135, v136, v137
	v_pk_fma_f32 v[140:141], v[76:77], v[194:195], v[140:141]
	v_cvt_pk_bf16_f32 v136, v138, v139
	v_pk_fma_f32 v[140:141], v[92:93], v[196:197], v[140:141]
	s_cmpk_eq_i32 s17, 0x780
	v_pk_fma_f32 v[140:141], v[96:97], v[142:143], v[140:141]
	s_nop 0
	v_cvt_pk_bf16_f32 v137, v140, v141
	ds_write_b128 v179, v[134:137]
	s_cbranch_scc1 .LBB0_867
	v_add_u32_e32 v132, s17, v162
	v_add_u32_e32 v106, 0x7d, v132
	v_mov_b64_e32 v[130:131], s[10:11]
	v_mad_i64_i32 v[106:107], s[14:15], v106, s3, v[130:131]
	s_lshl_b32 s12, s23, 1
	v_lshl_add_u64 v[106:107], v[106:107], 0, s[12:13]
	s_mov_b32 s12, s3
	v_lshl_add_u64 v[106:107], v[106:107], 0, v[202:203]
	v_add_co_u32_e32 v106, vcc, 0x2000, v106
	s_nop 1
	v_addc_co_u32_e32 v107, vcc, 0, v107, vcc
	v_lshl_add_u64 v[108:109], v[106:107], 0, s[12:13]
	v_lshl_add_u64 v[114:115], v[108:109], 0, s[12:13]
	v_lshl_add_u64 v[116:117], v[114:115], 0, s[12:13]
	v_lshl_add_u64 v[122:123], v[116:117], 0, s[12:13]
	v_lshl_add_u64 v[124:125], v[122:123], 0, s[12:13]
	v_lshl_add_u64 v[130:131], v[124:125], 0, s[12:13]
	global_load_dwordx4 v[110:113], v[106:107], off
	s_nop 0
	global_load_dwordx4 v[106:109], v[108:109], off
	global_load_dwordx4 v[118:121], v[114:115], off
	s_nop 0
	global_load_dwordx4 v[114:117], v[116:117], off
	s_nop 0
	global_load_dwordx4 v[126:129], v[122:123], off
	s_nop 0
	global_load_dwordx4 v[122:125], v[124:125], off
	s_nop 0
	global_load_dwordx4 v[130:133], v[130:131], off
.LBB0_867:
	v_lshl_add_u64 v[134:135], v[154:155], 0, v[150:151]
	s_mov_b32 s12, 0x29c02000
	v_lshl_add_u64 v[136:137], v[134:135], 0, s[12:13]
	global_load_ushort v190, v[136:137], off offset:1024
	s_mov_b32 s12, 0x29c04000
	v_lshl_add_u64 v[136:137], v[134:135], 0, s[12:13]
	global_load_ushort v189, v[136:137], off offset:3072
	s_mov_b32 s12, 0x29c07000
	v_lshl_add_u64 v[136:137], v[134:135], 0, s[12:13]
	global_load_ushort v188, v[136:137], off offset:1024
	s_mov_b32 s12, 0x29c09000
	v_lshl_add_u64 v[136:137], v[134:135], 0, s[12:13]
	global_load_ushort v187, v[136:137], off offset:3072
	s_mov_b32 s12, 0x29c0c000
	v_lshl_add_u64 v[136:137], v[134:135], 0, s[12:13]
	global_load_ushort v186, v[136:137], off offset:1024
	s_mov_b32 s12, 0x29c0e000
	v_lshl_add_u64 v[136:137], v[134:135], 0, s[12:13]
	global_load_ushort v185, v[136:137], off offset:3072
	s_mov_b32 s12, 0x29c11000
	v_lshl_add_u64 v[136:137], v[134:135], 0, s[12:13]
	global_load_ushort v183, v[136:137], off offset:1024
	s_mov_b32 s12, 0x29c13000
	v_lshl_add_u64 v[136:137], v[134:135], 0, s[12:13]
	global_load_ushort v184, v[136:137], off offset:3072
	s_waitcnt lgkmcnt(0)
	s_barrier
	ds_read_b128 v[134:137], v180
	ds_read_b128 v[192:195], v180 offset:64
	s_waitcnt lgkmcnt(1)
	v_mfma_f32_16x16x32_bf16 v[138:141], v[134:137], v[10:13], 0
	v_mfma_f32_16x16x32_bf16 v[142:145], v[134:137], v[14:17], 0
	v_mfma_f32_16x16x32_bf16 v[146:149], v[134:137], v[30:33], 0
	v_mfma_f32_16x16x32_bf16 v[134:137], v[134:137], v[50:53], 0
	s_waitcnt lgkmcnt(0)
	v_mfma_f32_16x16x32_bf16 v[138:141], v[192:195], v[2:5], v[138:141]
	v_mfma_f32_16x16x32_bf16 v[142:145], v[192:195], v[18:21], v[142:145]
	v_mfma_f32_16x16x32_bf16 v[146:149], v[192:195], v[38:41], v[146:149]
	v_mfma_f32_16x16x32_bf16 v[134:137], v[192:195], v[54:57], v[134:137]
	ds_read_b128 v[192:195], v180 offset:128
	s_waitcnt lgkmcnt(0)
	v_mfma_f32_16x16x32_bf16 v[138:141], v[192:195], v[6:9], v[138:141]
	v_mfma_f32_16x16x32_bf16 v[142:145], v[192:195], v[22:25], v[142:145]
	v_mfma_f32_16x16x32_bf16 v[196:199], v[192:195], v[42:45], v[146:149]
	v_mfma_f32_16x16x32_bf16 v[134:137], v[192:195], v[58:61], v[134:137]
	ds_read_b128 v[192:195], v180 offset:192
	s_waitcnt lgkmcnt(0)
	v_mfma_f32_16x16x32_bf16 v[146:149], v[192:195], v[34:37], v[138:141]
	s_nop 7
	v_add_f32_e32 v146, v156, v146
	v_mul_f32_e32 v146, 0xbfb8aa3b, v146
	v_exp_f32_e32 v146, v146
	v_mfma_f32_16x16x32_bf16 v[138:141], v[192:195], v[26:29], v[142:145]
	v_add_f32_e32 v146, 1.0, v146
	v_rcp_f32_e32 v146, v146
	v_mfma_f32_16x16x32_bf16 v[142:145], v[192:195], v[46:49], v[196:199]
	v_mul_f32_e32 v146, 0xc1000000, v146
	v_mul_f32_e32 v191, v160, v146
	v_mul_f32_e32 v146, 0x3fb8aa3b, v191
	v_mfma_f32_16x16x32_bf16 v[134:137], v[192:195], v[62:65], v[134:137]
	v_exp_f32_e32 v146, v146
	v_add_f32_e32 v192, v191, v191
	v_cmp_nlt_f32_e32 vcc, s1, v192
	s_and_saveexec_b64 s[14:15], vcc
	s_xor_b64 s[14:15], exec, s[14:15]
	v_fma_f32 v191, -v146, v146, 1.0
	s_andn2_saveexec_b64 s[14:15], s[14:15]
	v_fmamk_f32 v191, v192, 0x3ab60b61, v230
	v_fmaak_f32 v191, v192, v191, 0x3d2aaaab
	v_fmaak_f32 v191, v192, v191, 0x3e2aaaab
	v_fma_f32 v191, v192, v191, 0.5
	v_fma_f32 v191, v192, v191, 1.0
	v_mul_f32_e64 v191, v191, -v192
	s_or_b64 exec, exec, s[14:15]
	v_add_f32_e32 v142, v158, v142
	v_mul_f32_e32 v142, 0xbfb8aa3b, v142
	v_add_f32_e32 v147, v156, v147
	v_exp_f32_e32 v142, v142
	v_mul_f32_e32 v147, 0xbfb8aa3b, v147
	v_exp_f32_e32 v147, v147
	ds_read_u16 v192, v181
	v_add_f32_e32 v142, 1.0, v142
	v_rcp_f32_e32 v142, v142
	v_add_f32_e32 v147, 1.0, v147
	v_sqrt_f32_e32 v191, v191
	v_rcp_f32_e32 v147, v147
	s_waitcnt lgkmcnt(0)
	v_lshlrev_b32_e32 v192, 16, v192
	v_mul_f32_e32 v142, v142, v192
	v_mul_f32_e32 v191, v191, v142
	v_mul_f32_e32 v142, 0xc1000000, v147
	v_mul_f32_e32 v147, v160, v142
	v_mul_f32_e32 v142, 0x3fb8aa3b, v147
	s_and_b32 s12, s16, 64
	v_exp_f32_e32 v142, v142
	s_mulk_i32 s12, 0x240
	s_add_i32 s12, s12, 0
	v_add_f32_e32 v147, v147, v147
	v_lshl_add_u32 v193, v166, 2, s12
	v_cmp_nlt_f32_e32 vcc, s1, v147
	ds_write2st64_b32 v193, v146, v191 offset0:136 offset1:208
	s_and_saveexec_b64 s[14:15], vcc
	s_xor_b64 s[14:15], exec, s[14:15]
	v_fma_f32 v146, -v142, v142, 1.0
	s_andn2_saveexec_b64 s[14:15], s[14:15]
	v_fmamk_f32 v146, v147, 0x3ab60b61, v230
	v_fmaak_f32 v146, v147, v146, 0x3d2aaaab
	v_fmaak_f32 v146, v147, v146, 0x3e2aaaab
	v_fma_f32 v146, v147, v146, 0.5
	v_fma_f32 v146, v147, v146, 1.0
	v_mul_f32_e64 v146, v146, -v147
	s_or_b64 exec, exec, s[14:15]
	v_add_f32_e32 v143, v158, v143
	v_mul_f32_e32 v143, 0xbfb8aa3b, v143
	v_add_f32_e32 v148, v156, v148
	v_exp_f32_e32 v143, v143
	v_mul_f32_e32 v148, 0xbfb8aa3b, v148
	v_exp_f32_e32 v148, v148
	ds_read_u16 v147, v181 offset:272
	v_add_f32_e32 v143, 1.0, v143
	v_rcp_f32_e32 v143, v143
	v_add_f32_e32 v148, 1.0, v148
	v_sqrt_f32_e32 v146, v146
	v_rcp_f32_e32 v148, v148
	s_waitcnt lgkmcnt(0)
	v_lshlrev_b32_e32 v147, 16, v147
	v_mul_f32_e32 v143, v143, v147
	v_mul_f32_e32 v146, v146, v143
	v_mul_f32_e32 v143, 0xc1000000, v148
	v_mul_f32_e32 v147, v160, v143
	v_mul_f32_e32 v143, 0x3fb8aa3b, v147
	v_exp_f32_e32 v143, v143
	v_lshl_add_u32 v191, v167, 2, s12
	ds_write2st64_b32 v191, v142, v146 offset0:136 offset1:208
	v_add_f32_e32 v146, v147, v147
	v_cmp_nlt_f32_e32 vcc, s1, v146
	s_and_saveexec_b64 s[14:15], vcc
	s_xor_b64 s[14:15], exec, s[14:15]
	v_fma_f32 v142, -v143, v143, 1.0
	s_andn2_saveexec_b64 s[14:15], s[14:15]
	v_fmamk_f32 v142, v146, 0x3ab60b61, v230
	v_fmaak_f32 v142, v146, v142, 0x3d2aaaab
	v_fmaak_f32 v142, v146, v142, 0x3e2aaaab
	v_fma_f32 v142, v146, v142, 0.5
	v_fma_f32 v142, v146, v142, 1.0
	v_mul_f32_e64 v142, v142, -v146
	s_or_b64 exec, exec, s[14:15]
	v_add_f32_e32 v144, v158, v144
	v_mul_f32_e32 v144, 0xbfb8aa3b, v144
	v_add_f32_e32 v147, v156, v149
	v_exp_f32_e32 v144, v144
	v_mul_f32_e32 v147, 0xbfb8aa3b, v147
	v_exp_f32_e32 v147, v147
	ds_read_u16 v146, v181 offset:544
	v_add_f32_e32 v144, 1.0, v144
	v_rcp_f32_e32 v144, v144
	v_add_f32_e32 v147, 1.0, v147
	v_sqrt_f32_e32 v142, v142
	v_rcp_f32_e32 v147, v147
	s_waitcnt lgkmcnt(0)
	v_lshlrev_b32_e32 v146, 16, v146
	v_mul_f32_e32 v144, v144, v146
	v_mul_f32_e32 v144, v142, v144
	v_mul_f32_e32 v142, 0xc1000000, v147
	v_mul_f32_e32 v146, v160, v142
	v_mul_f32_e32 v142, 0x3fb8aa3b, v146
	v_exp_f32_e32 v142, v142
	v_lshl_add_u32 v148, v168, 2, s12
	ds_write2st64_b32 v148, v143, v144 offset0:136 offset1:208
	v_add_f32_e32 v144, v146, v146
	v_cmp_nlt_f32_e32 vcc, s1, v144
	s_and_saveexec_b64 s[14:15], vcc
	s_xor_b64 s[14:15], exec, s[14:15]
	v_fma_f32 v143, -v142, v142, 1.0
	s_andn2_saveexec_b64 s[14:15], s[14:15]
	v_fmamk_f32 v143, v144, 0x3ab60b61, v230
	v_fmaak_f32 v143, v144, v143, 0x3d2aaaab
	v_fmaak_f32 v143, v144, v143, 0x3e2aaaab
	v_fma_f32 v143, v144, v143, 0.5
	v_fma_f32 v143, v144, v143, 1.0
	v_mul_f32_e64 v143, v143, -v144
	s_or_b64 exec, exec, s[14:15]
	v_add_f32_e32 v144, v158, v145
	v_add_f32_e32 v138, v157, v138
	v_mul_f32_e32 v144, 0xbfb8aa3b, v144
	v_mul_f32_e32 v138, 0xbfb8aa3b, v138
	v_exp_f32_e32 v144, v144
	v_exp_f32_e32 v138, v138
	ds_read_u16 v145, v181 offset:816
	v_sqrt_f32_e32 v143, v143
	v_add_f32_e32 v144, 1.0, v144
	v_add_f32_e32 v138, 1.0, v138
	v_rcp_f32_e32 v144, v144
	v_rcp_f32_e32 v138, v138
	s_waitcnt lgkmcnt(0)
	v_lshlrev_b32_e32 v145, 16, v145
	v_lshl_add_u32 v146, v169, 2, s12
	v_mul_f32_e32 v144, v144, v145
	v_mul_f32_e32 v138, 0xc1000000, v138
	v_mul_f32_e32 v143, v143, v144
	v_mul_f32_e32 v144, v161, v138
	v_mul_f32_e32 v138, 0x3fb8aa3b, v144
	v_exp_f32_e32 v138, v138
	ds_write2st64_b32 v146, v142, v143 offset0:136 offset1:208
	v_add_f32_e32 v143, v144, v144
	v_cmp_nlt_f32_e32 vcc, s1, v143
	s_and_saveexec_b64 s[14:15], vcc
	s_xor_b64 s[14:15], exec, s[14:15]
	v_fma_f32 v142, -v138, v138, 1.0
	s_andn2_saveexec_b64 s[14:15], s[14:15]
	v_fmamk_f32 v142, v143, 0x3ab60b61, v230
	v_fmaak_f32 v142, v143, v142, 0x3d2aaaab
	v_fmaak_f32 v142, v143, v142, 0x3e2aaaab
	v_fma_f32 v142, v143, v142, 0.5
	v_fma_f32 v142, v143, v142, 1.0
	v_mul_f32_e64 v142, v142, -v143
	s_or_b64 exec, exec, s[14:15]
	v_add_f32_e32 v134, v159, v134
	v_mul_f32_e32 v134, 0xbfb8aa3b, v134
	v_add_f32_e32 v139, v157, v139
	v_exp_f32_e32 v134, v134
	v_mul_f32_e32 v139, 0xbfb8aa3b, v139
	v_exp_f32_e32 v139, v139
	ds_read_u16 v143, v182
	v_add_f32_e32 v134, 1.0, v134
	v_rcp_f32_e32 v134, v134
	v_add_f32_e32 v139, 1.0, v139
	v_sqrt_f32_e32 v142, v142
	v_rcp_f32_e32 v139, v139
	s_waitcnt lgkmcnt(0)
	v_lshlrev_b32_e32 v143, 16, v143
	v_mul_f32_e32 v134, v134, v143
	v_mul_f32_e32 v142, v142, v134
	v_mul_f32_e32 v134, 0xc1000000, v139
	v_mul_f32_e32 v139, v161, v134
	v_mul_f32_e32 v134, 0x3fb8aa3b, v139
	v_exp_f32_e32 v134, v134
	v_add_f32_e32 v139, v139, v139
	v_lshl_add_u32 v144, v170, 2, s12
	v_cmp_nlt_f32_e32 vcc, s1, v139
	ds_write2st64_b32 v144, v138, v142 offset0:136 offset1:208
	s_and_saveexec_b64 s[14:15], vcc
	s_xor_b64 s[14:15], exec, s[14:15]
	v_fma_f32 v138, -v134, v134, 1.0
	s_andn2_saveexec_b64 s[14:15], s[14:15]
	v_fmamk_f32 v138, v139, 0x3ab60b61, v230
	v_fmaak_f32 v138, v139, v138, 0x3d2aaaab
	v_fmaak_f32 v138, v139, v138, 0x3e2aaaab
	v_fma_f32 v138, v139, v138, 0.5
	v_fma_f32 v138, v139, v138, 1.0
	v_mul_f32_e64 v138, v138, -v139
	s_or_b64 exec, exec, s[14:15]
	v_add_f32_e32 v135, v159, v135
	v_mul_f32_e32 v135, 0xbfb8aa3b, v135
	v_add_f32_e32 v140, v157, v140
	v_exp_f32_e32 v135, v135
	v_mul_f32_e32 v140, 0xbfb8aa3b, v140
	v_exp_f32_e32 v140, v140
	ds_read_u16 v139, v182 offset:272
	v_add_f32_e32 v135, 1.0, v135
	v_rcp_f32_e32 v135, v135
	v_add_f32_e32 v140, 1.0, v140
	v_sqrt_f32_e32 v138, v138
	v_rcp_f32_e32 v140, v140
	s_waitcnt lgkmcnt(0)
	v_lshlrev_b32_e32 v139, 16, v139
	v_mul_f32_e32 v135, v135, v139
	v_mul_f32_e32 v138, v138, v135
	v_mul_f32_e32 v135, 0xc1000000, v140
	v_mul_f32_e32 v139, v161, v135
	v_mul_f32_e32 v135, 0x3fb8aa3b, v139
	v_exp_f32_e32 v135, v135
	v_lshl_add_u32 v142, v171, 2, s12
	ds_write2st64_b32 v142, v134, v138 offset0:136 offset1:208
	v_add_f32_e32 v138, v139, v139
	v_cmp_nlt_f32_e32 vcc, s1, v138
	s_and_saveexec_b64 s[14:15], vcc
	s_xor_b64 s[14:15], exec, s[14:15]
	v_fma_f32 v134, -v135, v135, 1.0
	s_andn2_saveexec_b64 s[14:15], s[14:15]
	v_fmamk_f32 v134, v138, 0x3ab60b61, v230
	v_fmaak_f32 v134, v138, v134, 0x3d2aaaab
	v_fmaak_f32 v134, v138, v134, 0x3e2aaaab
	v_fma_f32 v134, v138, v134, 0.5
	v_fma_f32 v134, v138, v134, 1.0
	v_mul_f32_e64 v134, v134, -v138
	s_or_b64 exec, exec, s[14:15]
	v_add_f32_e32 v136, v159, v136
	v_mul_f32_e32 v136, 0xbfb8aa3b, v136
	v_add_f32_e32 v139, v157, v141
	v_exp_f32_e32 v136, v136
	v_mul_f32_e32 v139, 0xbfb8aa3b, v139
	v_exp_f32_e32 v139, v139
	ds_read_u16 v138, v182 offset:544
	v_add_f32_e32 v136, 1.0, v136
	v_rcp_f32_e32 v136, v136
	v_add_f32_e32 v139, 1.0, v139
	v_sqrt_f32_e32 v134, v134
	v_rcp_f32_e32 v139, v139
	s_waitcnt lgkmcnt(0)
	v_lshlrev_b32_e32 v138, 16, v138
	v_mul_f32_e32 v136, v136, v138
	v_mul_f32_e32 v136, v134, v136
	v_mul_f32_e32 v134, 0xc1000000, v139
	v_mul_f32_e32 v138, v161, v134
	v_mul_f32_e32 v134, 0x3fb8aa3b, v138
	v_exp_f32_e32 v134, v134
	v_lshl_add_u32 v140, v172, 2, s12
	ds_write2st64_b32 v140, v135, v136 offset0:136 offset1:208
	v_add_f32_e32 v136, v138, v138
	v_cmp_nlt_f32_e32 vcc, s1, v136
	s_and_saveexec_b64 s[14:15], vcc
	s_xor_b64 s[14:15], exec, s[14:15]
	v_fma_f32 v135, -v134, v134, 1.0
	s_andn2_saveexec_b64 s[14:15], s[14:15]
	s_cbranch_execz .LBB0_864
	v_fmamk_f32 v135, v136, 0x3ab60b61, v230
	v_fmaak_f32 v135, v136, v135, 0x3d2aaaab
	v_fmaak_f32 v135, v136, v135, 0x3e2aaaab
	v_fma_f32 v135, v136, v135, 0.5
	v_fma_f32 v135, v136, v135, 1.0
	v_mul_f32_e64 v135, v135, -v136
	s_branch .LBB0_864

	.amdhsa_kernel _Z6mk_fwd4Args
		.amdhsa_group_segment_fixed_size 0
		.amdhsa_private_segment_fixed_size 0
		.amdhsa_kernarg_size 472
		.amdhsa_user_sgpr_count 2
		.amdhsa_user_sgpr_dispatch_ptr 0
		.amdhsa_user_sgpr_queue_ptr 0
		.amdhsa_user_sgpr_kernarg_segment_ptr 1
		.amdhsa_user_sgpr_dispatch_id 0
		.amdhsa_user_sgpr_kernarg_preload_length 0
		.amdhsa_user_sgpr_kernarg_preload_offset 0
		.amdhsa_user_sgpr_private_segment_size 0
		.amdhsa_uses_dynamic_stack 0
		.amdhsa_enable_private_segment 0
		.amdhsa_system_sgpr_workgroup_id_x 1
		.amdhsa_system_sgpr_workgroup_id_y 0
		.amdhsa_system_sgpr_workgroup_id_z 0
		.amdhsa_system_sgpr_workgroup_info 0
		.amdhsa_system_vgpr_workitem_id 0
				.amdhsa_next_free_vgpr 256
				.amdhsa_next_free_sgpr 102
				.amdhsa_accum_offset 256
		.amdhsa_reserve_vcc 1
		.amdhsa_float_round_mode_32 0
		.amdhsa_float_round_mode_16_64 0
		.amdhsa_float_denorm_mode_32 3
		.amdhsa_float_denorm_mode_16_64 3
		.amdhsa_dx10_clamp 1
		.amdhsa_ieee_mode 1
		.amdhsa_fp16_overflow 0
		.amdhsa_tg_split 0
		.amdhsa_exception_fp_ieee_invalid_op 0
		.amdhsa_exception_fp_denorm_src 0
		.amdhsa_exception_fp_ieee_div_zero 0
		.amdhsa_exception_fp_ieee_overflow 0
		.amdhsa_exception_fp_ieee_underflow 0
		.amdhsa_exception_fp_ieee_inexact 0
		.amdhsa_exception_int_div_zero 0
	.end_amdhsa_kernel

amdhsa.kernels:
  - .agpr_count:     0
    .args:
      - .offset:         0
        .size:           216
        .value_kind:     by_value
      - .offset:         216
        .size:           4
        .value_kind:     hidden_block_count_x
      - .offset:         220
        .size:           4
        .value_kind:     hidden_block_count_y
      - .offset:         224
        .size:           4
        .value_kind:     hidden_block_count_z
      - .offset:         228
        .size:           2
        .value_kind:     hidden_group_size_x
      - .offset:         230
        .size:           2
        .value_kind:     hidden_group_size_y
      - .offset:         232
        .size:           2
        .value_kind:     hidden_group_size_z
      - .offset:         234
        .size:           2
        .value_kind:     hidden_remainder_x
      - .offset:         236
        .size:           2
        .value_kind:     hidden_remainder_y
      - .offset:         238
        .size:           2
        .value_kind:     hidden_remainder_z
      - .offset:         256
        .size:           8
        .value_kind:     hidden_global_offset_x
      - .offset:         264
        .size:           8
        .value_kind:     hidden_global_offset_y
      - .offset:         272
        .size:           8
        .value_kind:     hidden_global_offset_z
      - .offset:         280
        .size:           2
        .value_kind:     hidden_grid_dims
      - .offset:         336
        .size:           4
        .value_kind:     hidden_dynamic_lds_size
    .group_segment_fixed_size: 0
    .kernarg_segment_align: 8
    .kernarg_segment_size: 472
    .language:       OpenCL C
    .language_version:
      - 2
      - 0
    .max_flat_workgroup_size: 512
    .name:           _Z6mk_fwd4Args
    .private_segment_fixed_size: 0
    .sgpr_count:     108
    .sgpr_spill_count: 124
    .symbol:         _Z6mk_fwd4Args.kd
    .uniform_work_group_size: 1
    .uses_dynamic_stack: false
    .vgpr_count:     256
    .vgpr_spill_count: 0
    .wavefront_size: 64
